# v73: MODE1 loop: waves 0-3 issue all 8 LDS-DMA pieces of a tile (waves 4-7 none) to balance the two waves of each SIMD
# speedup vs baseline: 1.0037x; 1.0037x over previous
; template <bool ONLINE, int NO>
; __device__ __forceinline__ void softmax_tile(f32x16 (&s)[2], float& m, float& l, f32x16 (&O)[NO], u32x4 (&pk)[4]) {
;     ...
;     float ps = 0.f;
; #pragma unroll
;     for (int blk = 0; blk < 2; ++blk)
; #pragma unroll
;         for (int i = 0; i < 16; ++i) { const float p = __builtin_amdgcn_exp2f(ONLINE ? (s[blk][i] - mn) : s[blk][i]); ps += p; s[blk][i] = p; }
;     l += ps;
; #pragma unroll
;     for (int blk = 0; blk < 2; ++blk)
; #pragma unroll
;         for (int sh = 0; sh < 2; ++sh) { u32x4 pw;
;             pw.x = cvt_pk_bf16(s[blk][8 * sh], s[blk][8 * sh + 1]); pw.y = cvt_pk_bf16(s[blk][8 * sh + 2], s[blk][8 * sh + 3]);
;             pw.z = cvt_pk_bf16(s[blk][8 * sh + 4], s[blk][8 * sh + 5]); pw.w = cvt_pk_bf16(s[blk][8 * sh + 6], s[blk][8 * sh + 7]); pk[2 * blk + sh] = pw; }
.LBB0_473:
	s_nop 7
	v_exp_f32_e32 v14, v96
	v_exp_f32_e32 v15, v97
	v_exp_f32_e32 v168, v98
	v_exp_f32_e32 v169, v99
	v_exp_f32_e32 v170, v100
	v_exp_f32_e32 v171, v101
	v_exp_f32_e32 v172, v102
	v_exp_f32_e32 v173, v103
	v_exp_f32_e32 v180, v108
	v_exp_f32_e32 v181, v109
	v_exp_f32_e32 v182, v110
	v_exp_f32_e32 v183, v111
	v_cvt_pk_bf16_f32 v108, v14, v15
	v_cvt_pk_bf16_f32 v109, v168, v169
	v_cvt_pk_bf16_f32 v110, v170, v171
	v_cvt_pk_bf16_f32 v111, v172, v173
	v_add_f32_e32 v14, 0, v14
	v_exp_f32_e32 v174, v104
	v_exp_f32_e32 v175, v105
	v_exp_f32_e32 v176, v106
	v_exp_f32_e32 v177, v107
	v_exp_f32_e32 v192, v88
	v_exp_f32_e32 v193, v89
	v_exp_f32_e32 v194, v90
	v_exp_f32_e32 v195, v91
	v_exp_f32_e32 v196, v92
	v_exp_f32_e32 v197, v93
	v_exp_f32_e32 v198, v94
	v_exp_f32_e32 v199, v95
	ds_read_b64_tr_b16 v[104:105], v0 offset:0x2000
	ds_read_b64_tr_b16 v[106:107], v0 offset:0x2100
	ds_read_b64_tr_b16 v[96:97], v0 offset:0x2200
	ds_read_b64_tr_b16 v[98:99], v0 offset:0x2300
	ds_read_b64_tr_b16 v[92:93], v0 offset:0x2400
	ds_read_b64_tr_b16 v[94:95], v0 offset:0x2500
	ds_read_b64_tr_b16 v[88:89], v0 offset:0x2600
	ds_read_b64_tr_b16 v[90:91], v0 offset:0x2700
	s_waitcnt lgkmcnt(15)
	v_add_f32_e32 v14, v15, v14
	v_mfma_f32_32x32x16_bf16 v[64:79], v[144:147], v[108:111], v[64:79]
	v_add_f32_e32 v14, v168, v14
	v_add_f32_e32 v14, v169, v14
	v_add_f32_e32 v14, v170, v14
	v_add_f32_e32 v14, v171, v14
	v_add_f32_e32 v14, v172, v14
	v_add_f32_e32 v14, v173, v14
	v_cvt_pk_bf16_f32 v100, v174, v175
	v_mfma_f32_32x32x16_bf16 v[48:63], v[140:143], v[108:111], v[48:63]
	v_cvt_pk_bf16_f32 v101, v176, v177
	v_cvt_pk_bf16_f32 v102, v180, v181
	v_cvt_pk_bf16_f32 v103, v182, v183
	v_add_f32_e32 v14, v174, v14
	v_add_f32_e32 v14, v175, v14
	v_add_f32_e32 v14, v176, v14
	v_add_f32_e32 v14, v177, v14
	v_mfma_f32_32x32x16_bf16 v[32:47], v[136:139], v[108:111], v[32:47]
	v_exp_f32_e32 v184, v80
	v_exp_f32_e32 v185, v81
	v_exp_f32_e32 v186, v82
	v_exp_f32_e32 v187, v83
	v_exp_f32_e32 v188, v84
	v_exp_f32_e32 v189, v85
	v_exp_f32_e32 v190, v86
	v_mfma_f32_32x32x16_bf16 v[16:31], v[132:135], v[108:111], v[16:31]
	ds_read_b64_tr_b16 v[140:141], v0 offset:0x3000
	ds_read_b64_tr_b16 v[142:143], v0 offset:0x3100
	ds_read_b64_tr_b16 v[136:137], v0 offset:0x3200
	ds_read_b64_tr_b16 v[138:139], v0 offset:0x3300
	ds_read_b64_tr_b16 v[132:133], v0 offset:0x3400
	ds_read_b64_tr_b16 v[134:135], v0 offset:0x3500
	ds_read_b64_tr_b16 v[108:109], v0 offset:0x3600
	ds_read_b64_tr_b16 v[110:111], v0 offset:0x3700
	s_waitcnt lgkmcnt(15)
	v_exp_f32_e32 v191, v87
	v_add_f32_e32 v14, v180, v14
	v_add_f32_e32 v14, v181, v14
	v_add_f32_e32 v14, v182, v14
	v_add_f32_e32 v14, v183, v14
	v_mfma_f32_32x32x16_bf16 v[64:79], v[128:131], v[100:103], v[64:79]
	v_cvt_pk_bf16_f32 v84, v184, v185
	v_cvt_pk_bf16_f32 v85, v186, v187
	v_cvt_pk_bf16_f32 v86, v188, v189
	v_cvt_pk_bf16_f32 v87, v190, v191
	v_add_f32_e32 v14, v184, v14
	v_add_f32_e32 v14, v185, v14
	s_waitcnt lgkmcnt(8)
	v_mfma_f32_32x32x16_bf16 v[48:63], v[10:13], v[100:103], v[48:63]
	v_add_f32_e32 v14, v186, v14
	v_add_f32_e32 v14, v187, v14
	v_add_f32_e32 v14, v188, v14
	v_add_f32_e32 v14, v189, v14
	v_add_f32_e32 v14, v190, v14
	v_add_f32_e32 v14, v191, v14
	v_cvt_pk_bf16_f32 v80, v192, v193
	v_mfma_f32_32x32x16_bf16 v[32:47], v[6:9], v[100:103], v[32:47]
	v_cvt_pk_bf16_f32 v81, v194, v195
	v_cvt_pk_bf16_f32 v82, v196, v197
	v_cvt_pk_bf16_f32 v83, v198, v199
	v_add_f32_e32 v14, v192, v14
	v_add_f32_e32 v14, v193, v14
	s_waitcnt lgkmcnt(0)
	v_add_f32_e32 v14, v194, v14
	v_mfma_f32_32x32x16_bf16 v[16:31], v[2:5], v[100:103], v[16:31]
	v_add_f32_e32 v14, v195, v14
	v_add_f32_e32 v14, v196, v14
	v_add_f32_e32 v14, v197, v14
	v_add_f32_e32 v14, v198, v14
	v_add_f32_e32 v14, v199, v14
	v_add_f32_e32 v163, v163, v14
	s_add_i32 s41, s40, 3
	s_cmp_ge_u32 s41, s22
	s_cbranch_scc1 .Lm1_tail_nodma
	s_cmpk_gt_u32 s58, 0xff
	s_cbranch_scc1 .Lm1_tail_nodma
	v_mfma_f32_32x32x16_bf16 v[64:79], v[104:107], v[84:87], v[64:79]
	s_mov_b64 s[70:71], 0x1000
	s_add_i32 s41, s38, 0x18000
	s_and_b32 s41, s41, 0x18000
	s_add_i32 s41, s77, s41
	v_mfma_f32_32x32x16_bf16 v[48:63], v[96:99], v[84:87], v[48:63]
	v_lshl_add_u64 v[240:241], v[152:153], 0, s[68:69]
	v_lshl_add_u64 v[242:243], v[240:241], 0, s[42:43]
	s_mov_b32 m0, s41
	v_lshl_add_u64 v[240:241], v[240:241], 0, s[44:45]
	v_mfma_f32_32x32x16_bf16 v[32:47], v[92:95], v[84:87], v[32:47]
	global_load_lds_dwordx4 v[242:243], off
	s_add_i32 m0, s41, 0x1000
	v_lshl_add_u64 v[242:243], v[242:243], 0, s[70:71]
	global_load_lds_dwordx4 v[242:243], off
	v_mfma_f32_32x32x16_bf16 v[16:31], v[88:91], v[84:87], v[16:31]
	s_add_i32 m0, s41, 0x2000
	v_lshl_add_u64 v[242:243], v[240:241], 0, s[70:71]
	global_load_lds_dwordx4 v[240:241], off
	s_add_i32 m0, s41, 0x3000
	v_mfma_f32_32x32x16_bf16 v[64:79], v[140:143], v[80:83], v[64:79]
	v_lshl_add_u64 v[240:241], v[154:155], 0, s[68:69]
	global_load_lds_dwordx4 v[242:243], off
	v_lshl_add_u64 v[242:243], v[240:241], 0, s[48:49]
	s_add_i32 m0, s41, 0x4000
	v_mfma_f32_32x32x16_bf16 v[48:63], v[136:139], v[80:83], v[48:63]
	v_lshl_add_u64 v[240:241], v[240:241], 0, s[50:51]
	global_load_lds_dwordx4 v[242:243], off
	s_add_i32 m0, s41, 0x5000
	v_lshl_add_u64 v[242:243], v[242:243], 0, s[70:71]
	v_mfma_f32_32x32x16_bf16 v[32:47], v[132:135], v[80:83], v[32:47]
	global_load_lds_dwordx4 v[242:243], off
	s_add_i32 m0, s41, 0x6000
	v_lshl_add_u64 v[242:243], v[240:241], 0, s[70:71]
	global_load_lds_dwordx4 v[240:241], off
	s_add_i32 m0, s41, 0x7000
	s_nop 0
	global_load_lds_dwordx4 v[242:243], off
	v_mfma_f32_32x32x16_bf16 v[16:31], v[108:111], v[80:83], v[16:31]
	s_branch .LBB0_474

; #define ATT_WAITV(n) asm volatile("s_waitcnt vmcnt(" #n ")" ::: "memory")
; template <int MODE>
; __device__ __forceinline__ void attn_unit(const Params& P, LAS unsigned char* lds, const int b, const int h, const int qb) {
;     ...
;         if (kt + 2 < nt) { if (FOX) ATT_WAITV(10); else ATT_WAITV(8); } else if (kt + 1 < nt) { if (FOX) ATT_WAITV(5); else ATT_WAITV(4); } else ATT_WAITV(0);
;         __builtin_amdgcn_s_barrier(); asm volatile("" ::: "memory");
.LBB0_475:
	s_add_i32 s41, s40, 2
	s_cmp_ge_u32 s41, s22
	s_mov_b64 s[70:71], -1
	s_cbranch_scc0 .LBB0_481
	s_add_i32 s41, s40, 1
	s_cmp_ge_u32 s41, s22
	s_cbranch_scc0 .LBB0_478
	s_waitcnt vmcnt(0)
	s_mov_b64 s[70:71], 0
.LBB0_478:
	s_andn2_b64 vcc, exec, s[70:71]
	s_cbranch_vccnz .LBB0_480
	s_waitcnt vmcnt(8)
.LBB0_480:
	s_mov_b64 s[70:71], 0
.LBB0_481:
	s_andn2_b64 vcc, exec, s[70:71]
	s_cbranch_vccnz .LBB0_483
	s_waitcnt vmcnt(16)

; #define ATT_WAITV(n) asm volatile("s_waitcnt vmcnt(" #n ")" ::: "memory")
; template <int MODE>
; __device__ __forceinline__ void attn_unit(const Params& P, LAS unsigned char* lds, const int b, const int h, const int qb) {
;     ...
;     const int pr = (r & 19) | ((r & 4) << 1) | ((r & 8) >> 1);
;     const unsigned kra = pr * 256, kswz = pr & 15;
;     const unsigned vra = 16384 + hh * 2048 + ((lane & 15) >> 2) * 64 + ((lane >> 4) & 1) * 32 + (lane & 3) * 8;
;     f32x16 O[4];
; #pragma unroll
;     for (int d = 0; d < 4; ++d)
; #pragma unroll
;         for (int i = 0; i < 16; ++i) O[d][i] = 0.f;
;     float m1 = ONLINE ? -INFINITY : 0.f, l1 = 0.f;
;     const int ktw_last = (q0w + 31) / 64;
;     ATT_WAITV(0); __builtin_amdgcn_s_barrier(); asm volatile("" ::: "memory");
; #pragma unroll
;     for (int i = 0; i < AL_PD; ++i) if (kt0 + i < nt) ATT_DMA(kt0 + i, i);
;     for (int kt = kt0; kt < nt; ++kt) {
;         const int rel = kt - kt0, cur = rel & (AL_NBUF - 1);
;         if (kt + 2 < nt) { if (FOX) ATT_WAITV(10); else ATT_WAITV(8); } else if (kt + 1 < nt) { if (FOX) ATT_WAITV(5); else ATT_WAITV(4); } else ATT_WAITV(0);
;         __builtin_amdgcn_s_barrier(); asm volatile("" ::: "memory");
;         if (kt + AL_PD < nt) ATT_DMA(kt + AL_PD, (rel + AL_PD) & (AL_NBUF - 1));
.Lm1_skip:
	s_add_i32 s41, s40, 3
	s_cmp_ge_u32 s41, s22
	s_cbranch_scc1 .LBB0_474
	s_cmpk_gt_u32 s58, 0xff
	s_cbranch_scc1 .LBB0_474
	s_mov_b64 s[70:71], 0x1000
	s_add_i32 s41, s38, 0x18000
	s_and_b32 s41, s41, 0x18000
	s_add_i32 s41, s77, s41
	v_lshl_add_u64 v[2:3], v[152:153], 0, s[68:69]
	v_lshl_add_u64 v[4:5], v[2:3], 0, s[42:43]
	s_mov_b32 m0, s41
	v_lshl_add_u64 v[2:3], v[2:3], 0, s[44:45]
	global_load_lds_dwordx4 v[4:5], off
	s_add_i32 m0, s41, 0x1000
	v_lshl_add_u64 v[4:5], v[4:5], 0, s[70:71]
	global_load_lds_dwordx4 v[4:5], off
	s_add_i32 m0, s41, 0x2000
	v_lshl_add_u64 v[4:5], v[2:3], 0, s[70:71]
	global_load_lds_dwordx4 v[2:3], off
	s_add_i32 m0, s41, 0x3000
	v_lshl_add_u64 v[2:3], v[154:155], 0, s[68:69]
	global_load_lds_dwordx4 v[4:5], off
	v_lshl_add_u64 v[4:5], v[2:3], 0, s[48:49]
	s_add_i32 m0, s41, 0x4000
	v_lshl_add_u64 v[2:3], v[2:3], 0, s[50:51]
	global_load_lds_dwordx4 v[4:5], off
	s_add_i32 m0, s41, 0x5000
	v_lshl_add_u64 v[4:5], v[4:5], 0, s[70:71]
	global_load_lds_dwordx4 v[4:5], off
	s_add_i32 m0, s41, 0x6000
	v_lshl_add_u64 v[4:5], v[2:3], 0, s[70:71]
	global_load_lds_dwordx4 v[2:3], off
	s_add_i32 m0, s41, 0x7000
	s_nop 0
	global_load_lds_dwordx4 v[4:5], off
	s_branch .LBB0_474
; template <int MODE>
; __device__ __forceinline__ void attn_unit(const Params& P, LAS unsigned char* lds, const int b, const int h, const int qb) {
;     ...
;             if constexpr (MODE == 1) {
;                 bf16x8 kf[8];
;                 const unsigned kb_ = (unsigned)(uintptr_t)Kb + kra, c0 = mp * 8 + hh;
;                 k_issue4(kf, kb_ + (((c0) ^ kswz) << 4), kb_ + (((c0 + 2) ^ kswz) << 4), kb_ + (((c0 + 4) ^ kswz) << 4), kb_ + (((c0 + 6) ^ kswz) << 4));
;                 v_issue<0>(va, vaddr);
;                 k_wait<8>(kf);
; #pragma unroll
;                 for (int ks = 0; ks < 4; ++ks) { s[0] = MFMA32(kf[2 * ks], Qf[ks], s[0]); s[1] = MFMA32(kf[2 * ks + 1], Qf[ks], s[1]); }
;                 v_issue<1>(vb, vaddr);
;             } else {
; #pragma unroll
;             for (int ks = 0; ks < NQ; ++ks) {
;                 const unsigned chunk = mp * 8 + 2 * ks + hh;
;                 const unsigned off = kra + ((chunk ^ kswz) << 4);
;                 const bf16x8 a0 = *(const LAS bf16x8*)(Kb + off), a1 = *(const LAS bf16x8*)(Kb + off + 8192);
;                 s[0] = MFMA32(a0, Qf[ks], s[0]); s[1] = MFMA32(a1, Qf[ks], s[1]);
;             }
;             v_issue<0>(va, vaddr);
;             }
;             if (FOX) {
;                 const LAS float* cl = (const LAS float*)(lds + AL_CLS + (cur * 8 + w) * 256) + 8 * hh;
; #pragma unroll
;                 for (int blk = 0; blk < 2; ++blk)
; #pragma unroll
;                     for (int j4 = 0; j4 < 4; ++j4) { const f32x4 c = *(const LAS f32x4*)(cl + 32 * blk + 16 * (j4 >> 1) + 4 * (j4 & 1));
; #pragma unroll
;                         for (int e = 0; e < 4; ++e) s[blk][4 * j4 + e] -= c[e]; }
;             } else if (q0w - kt * 64 - 63 < 128) {
;                 const LAS float* bl = (const LAS float*)(lds + AL_BIAS);
; #pragma unroll
;                 for (int blk = 0; blk < 2; ++blk)
; #pragma unroll
;                     for (int i = 0; i < 16; ++i) { const int dist = q - (kbase + 32 * blk + 16 * (i >> 3) + (i & 7)); const int di = dist < 0 ? 0 : (dist > 128 ? 128 : dist); s[blk][i] += bl[di]; }
;             }
;             if (kt * 64 + 63 > q0w) {
; #pragma unroll
;                 for (int blk = 0; blk < 2; ++blk)
; #pragma unroll
;                     for (int i = 0; i < 16; ++i) { if (kbase + 32 * blk + 16 * (i >> 3) + (i & 7) > q) s[blk][i] = -INFINITY; }
;             }
.Lm1_fast:
	v_mfma_f32_32x32x16_bf16 v[96:111], v[2:5], v[112:115], 0
	v_mfma_f32_32x32x16_bf16 v[96:111], v[10:13], v[116:119], v[96:111]
	v_mfma_f32_32x32x16_bf16 v[96:111], v[168:171], v[120:123], v[96:111]
	v_mfma_f32_32x32x16_bf16 v[96:111], v[180:183], v[124:127], v[96:111]
	ds_read_b64_tr_b16 v[168:169], v0 offset:0x1000
	ds_read_b64_tr_b16 v[170:171], v0 offset:0x1100
	ds_read_b64_tr_b16 v[10:11], v0 offset:0x1200
	ds_read_b64_tr_b16 v[12:13], v0 offset:0x1300
	ds_read_b64_tr_b16 v[180:181], v0 offset:0x1400
	ds_read_b64_tr_b16 v[182:183], v0 offset:0x1500
	ds_read_b64_tr_b16 v[2:3], v0 offset:0x1600
	ds_read_b64_tr_b16 v[4:5], v0 offset:0x1700
	v_mfma_f32_32x32x16_bf16 v[80:95], v[6:9], v[112:115], 0
	s_nop 2
	v_exp_f32_e32 v14, v96
	v_exp_f32_e32 v15, v97
	v_mfma_f32_32x32x16_bf16 v[80:95], v[128:131], v[116:119], v[80:95]
	v_exp_f32_e32 v240, v98
	v_exp_f32_e32 v241, v99
	v_exp_f32_e32 v242, v100
	v_mfma_f32_32x32x16_bf16 v[80:95], v[172:175], v[120:123], v[80:95]
	v_exp_f32_e32 v243, v101
	v_exp_f32_e32 v244, v102
	v_exp_f32_e32 v245, v103
	v_mfma_f32_32x32x16_bf16 v[80:95], v[184:187], v[124:127], v[80:95]
	v_cvt_pk_bf16_f32 v96, v14, v15
	v_cvt_pk_bf16_f32 v97, v240, v241
	v_cvt_pk_bf16_f32 v98, v242, v243
	v_cvt_pk_bf16_f32 v99, v244, v245
	v_exp_f32_e32 v246, v104
	s_waitcnt lgkmcnt(8)
	v_mfma_f32_32x32x16_bf16 v[64:79], v[144:147], v[96:99], v[64:79]
	ds_read_b64_tr_b16 v[6:7], v0 offset:0x2000
	ds_read_b64_tr_b16 v[8:9], v0 offset:0x2100
	ds_read_b64_tr_b16 v[128:129], v0 offset:0x2200
	ds_read_b64_tr_b16 v[130:131], v0 offset:0x2300
	ds_read_b64_tr_b16 v[172:173], v0 offset:0x2400
	ds_read_b64_tr_b16 v[174:175], v0 offset:0x2500
	ds_read_b64_tr_b16 v[184:185], v0 offset:0x2600
	ds_read_b64_tr_b16 v[186:187], v0 offset:0x2700
	v_mfma_f32_32x32x16_bf16 v[48:63], v[140:143], v[96:99], v[48:63]
	v_exp_f32_e32 v247, v105
	v_exp_f32_e32 v248, v106
	v_exp_f32_e32 v249, v107
	v_mfma_f32_32x32x16_bf16 v[32:47], v[136:139], v[96:99], v[32:47]
	v_exp_f32_e32 v250, v108
	v_exp_f32_e32 v251, v109
	v_exp_f32_e32 v252, v110
	v_mfma_f32_32x32x16_bf16 v[16:31], v[132:135], v[96:99], v[16:31]
	v_exp_f32_e32 v253, v111
	v_add_f32_e32 v14, v15, v14
	v_cvt_pk_bf16_f32 v100, v246, v247
	v_cvt_pk_bf16_f32 v101, v248, v249
	v_cvt_pk_bf16_f32 v102, v250, v251
	v_add_f32_e32 v14, v240, v14
	v_cvt_pk_bf16_f32 v103, v252, v253
	v_add_f32_e32 v14, v241, v14
	s_waitcnt lgkmcnt(8)
	v_mfma_f32_32x32x16_bf16 v[64:79], v[168:171], v[100:103], v[64:79]
	ds_read_b64_tr_b16 v[144:145], v0 offset:0x3000
	ds_read_b64_tr_b16 v[146:147], v0 offset:0x3100
	ds_read_b64_tr_b16 v[140:141], v0 offset:0x3200
	ds_read_b64_tr_b16 v[142:143], v0 offset:0x3300
	ds_read_b64_tr_b16 v[136:137], v0 offset:0x3400
	ds_read_b64_tr_b16 v[138:139], v0 offset:0x3500
	ds_read_b64_tr_b16 v[132:133], v0 offset:0x3600
	ds_read_b64_tr_b16 v[134:135], v0 offset:0x3700
	v_mfma_f32_32x32x16_bf16 v[48:63], v[10:13], v[100:103], v[48:63]
	v_exp_f32_e32 v104, v80
	v_exp_f32_e32 v105, v81
	v_exp_f32_e32 v106, v82
	v_mfma_f32_32x32x16_bf16 v[32:47], v[180:183], v[100:103], v[32:47]
	v_exp_f32_e32 v107, v83
	v_exp_f32_e32 v108, v84
	v_exp_f32_e32 v109, v85
	v_mfma_f32_32x32x16_bf16 v[16:31], v[2:5], v[100:103], v[16:31]
	v_exp_f32_e32 v110, v86
	v_exp_f32_e32 v111, v87
	v_cvt_pk_bf16_f32 v80, v104, v105
	v_cvt_pk_bf16_f32 v81, v106, v107
	v_cvt_pk_bf16_f32 v82, v108, v109
	v_add_f32_e32 v14, v242, v14
	v_cvt_pk_bf16_f32 v83, v110, v111
	v_add_f32_e32 v14, v243, v14
	s_waitcnt lgkmcnt(8)
	v_mfma_f32_32x32x16_bf16 v[64:79], v[6:9], v[80:83], v[64:79]
	v_exp_f32_e32 v2, v88
	v_exp_f32_e32 v3, v89
	v_exp_f32_e32 v4, v90
	v_mfma_f32_32x32x16_bf16 v[48:63], v[128:131], v[80:83], v[48:63]
	v_exp_f32_e32 v5, v91
	v_exp_f32_e32 v10, v92
	v_exp_f32_e32 v11, v93
	v_mfma_f32_32x32x16_bf16 v[32:47], v[172:175], v[80:83], v[32:47]
	v_exp_f32_e32 v12, v94
	v_exp_f32_e32 v13, v95
	v_add_f32_e32 v14, v244, v14
	v_add_f32_e32 v14, v245, v14
	v_mfma_f32_32x32x16_bf16 v[16:31], v[184:187], v[80:83], v[16:31]
	v_cvt_pk_bf16_f32 v84, v2, v3
	v_cvt_pk_bf16_f32 v85, v4, v5
	v_cvt_pk_bf16_f32 v86, v10, v11
	v_add_f32_e32 v14, v246, v14
	v_cvt_pk_bf16_f32 v87, v12, v13
	v_add_f32_e32 v14, v247, v14
	v_add_f32_e32 v14, v248, v14
	s_waitcnt lgkmcnt(0)
	v_add_f32_e32 v14, v249, v14
	v_add_f32_e32 v14, v250, v14
	v_add_f32_e32 v14, v251, v14
	v_add_f32_e32 v14, v252, v14
	v_add_f32_e32 v14, v253, v14
	s_add_i32 s41, s40, 3
	s_cmp_ge_u32 s41, s22
	s_cbranch_scc1 .Lm1f_nodma
	s_cmpk_gt_u32 s58, 0xff
	s_cbranch_scc1 .Lm1f_nodma
	v_mfma_f32_32x32x16_bf16 v[64:79], v[144:147], v[84:87], v[64:79]
	s_mov_b64 s[70:71], 0x1000
	s_add_i32 s41, s38, 0x18000
	s_and_b32 s41, s41, 0x18000
	s_add_i32 s41, s77, s41
	v_lshl_add_u64 v[240:241], v[152:153], 0, s[68:69]
	v_lshl_add_u64 v[242:243], v[240:241], 0, s[42:43]
	s_mov_b32 m0, s41
	v_lshl_add_u64 v[240:241], v[240:241], 0, s[44:45]
	global_load_lds_dwordx4 v[242:243], off
	v_mfma_f32_32x32x16_bf16 v[48:63], v[140:143], v[84:87], v[48:63]
	s_add_i32 m0, s41, 0x1000
	v_lshl_add_u64 v[242:243], v[242:243], 0, s[70:71]
	global_load_lds_dwordx4 v[242:243], off
	s_add_i32 m0, s41, 0x2000
	v_lshl_add_u64 v[242:243], v[240:241], 0, s[70:71]
	global_load_lds_dwordx4 v[240:241], off
	s_add_i32 m0, s41, 0x3000
	v_lshl_add_u64 v[240:241], v[154:155], 0, s[68:69]
	global_load_lds_dwordx4 v[242:243], off
	v_add_f32_e32 v14, v104, v14
	v_add_f32_e32 v14, v105, v14
	v_add_f32_e32 v14, v106, v14
	v_add_f32_e32 v14, v107, v14
	v_mfma_f32_32x32x16_bf16 v[32:47], v[136:139], v[84:87], v[32:47]
	v_lshl_add_u64 v[242:243], v[240:241], 0, s[48:49]
	s_add_i32 m0, s41, 0x4000
	v_lshl_add_u64 v[240:241], v[240:241], 0, s[50:51]
	global_load_lds_dwordx4 v[242:243], off
	s_add_i32 m0, s41, 0x5000
	v_lshl_add_u64 v[242:243], v[242:243], 0, s[70:71]
	global_load_lds_dwordx4 v[242:243], off
	v_add_f32_e32 v14, v108, v14
	v_add_f32_e32 v14, v109, v14
	v_add_f32_e32 v14, v110, v14
	v_add_f32_e32 v14, v111, v14
	v_add_f32_e32 v14, v2, v14
	v_add_f32_e32 v14, v3, v14
	v_mfma_f32_32x32x16_bf16 v[16:31], v[132:135], v[84:87], v[16:31]
	s_add_i32 m0, s41, 0x6000
	v_lshl_add_u64 v[242:243], v[240:241], 0, s[70:71]
	global_load_lds_dwordx4 v[240:241], off
	s_add_i32 m0, s41, 0x7000
	s_nop 0
	global_load_lds_dwordx4 v[242:243], off
	v_add_f32_e32 v14, v4, v14
	v_add_f32_e32 v14, v5, v14
	v_add_f32_e32 v14, v10, v14
	v_add_f32_e32 v14, v11, v14
	v_add_f32_e32 v14, v12, v14
	v_add_f32_e32 v14, v13, v14
	v_add_f32_e32 v163, v163, v14
	s_branch .LBB0_474
